# norm phases: row-0 D loads issued together with the row-0 residual-stream loads (one latency round trip per loop iteration instead of two)
# speedup vs baseline: 1.0080x; 1.0080x over previous
.LBB0_358:
	s_waitcnt vmcnt(1)
	v_add_co_u32_e32 v8, vcc, 0x8000000, v100
	s_nop 1
	v_addc_co_u32_e32 v9, vcc, 0, v101, vcc
	s_waitcnt lgkmcnt(0)
	global_load_dwordx4 v[4:7], v[8:9], off
	global_load_dwordx4 v[28:31], v[8:9], off offset:1024
	s_brev_b32 s2, 48
	v_add_co_u32_e32 v24, vcc, s2, v100
	s_nop 1
	v_addc_co_u32_e32 v25, vcc, 0, v101, vcc
	global_load_dwordx4 v[20:23], v[24:25], off
	s_nop 0
	global_load_dwordx4 v[24:27], v[24:25], off offset:1024
	s_add_i32 s8, s60, 1
	s_ashr_i32 s9, s8, 31
	s_lshl_b64 s[8:9], s[8:9], 11
	v_lshl_add_u64 v[244:245], v[86:87], 0, s[8:9]
	global_load_dwordx4 v[228:231], v[244:245], off
	global_load_dwordx4 v[232:235], v[244:245], off offset:1024
	global_load_dwordx4 v[236:239], v[244:245], off offset:2048
	global_load_dwordx4 v[240:243], v[244:245], off offset:3072
	s_waitcnt vmcnt(7)
	v_lshlrev_b32_e32 v16, 16, v4
	v_and_b32_e32 v17, 0xffff0000, v4
	v_lshlrev_b32_e32 v18, 16, v5
	v_and_b32_e32 v19, 0xffff0000, v5
	v_lshlrev_b32_e32 v12, 16, v6
	v_and_b32_e32 v13, 0xffff0000, v6
	v_lshlrev_b32_e32 v14, 16, v7
	v_and_b32_e32 v15, 0xffff0000, v7
	s_waitcnt vmcnt(6)
	v_lshlrev_b32_e32 v8, 16, v28
	v_and_b32_e32 v9, 0xffff0000, v28
	v_lshlrev_b32_e32 v10, 16, v29
	v_and_b32_e32 v11, 0xffff0000, v29
	v_lshlrev_b32_e32 v4, 16, v30
	v_and_b32_e32 v5, 0xffff0000, v30
	v_lshlrev_b32_e32 v6, 16, v31
	v_and_b32_e32 v7, 0xffff0000, v31

.Lnm_nomul:
	v_cndmask_b32_e64 v28, 0, 1, s[22:23]
	s_and_b64 vcc, exec, s[0:1]
	s_cbranch_vccz .Lnm_d0done
	s_brev_b32 s2, 48
	v_add_co_u32_e32 v24, vcc, s2, v100
	s_nop 1
	v_addc_co_u32_e32 v25, vcc, 0, v101, vcc
	global_load_dwordx4 v[20:23], v[24:25], off
	s_nop 0
	global_load_dwordx4 v[24:27], v[24:25], off offset:1024
.Lnm_d0done:
	s_add_i32 s8, s60, 1
	s_ashr_i32 s9, s8, 31
	s_lshl_b64 s[8:9], s[8:9], 11
	v_lshl_add_u64 v[200:201], v[0:1], 0, s[8:9]
	s_mov_b64 s[8:9], 0x1000
	v_lshl_add_u64 v[202:203], v[200:201], 0, s[8:9]
	global_load_dwordx4 v[204:207], v[200:201], off
	global_load_dwordx4 v[208:211], v[200:201], off offset:1024
	global_load_dwordx4 v[212:215], v[200:201], off offset:2048
	global_load_dwordx4 v[216:219], v[200:201], off offset:3072
	global_load_dwordx4 v[220:223], v[202:203], off
	global_load_dwordx4 v[224:227], v[202:203], off offset:1024
	v_cmp_ne_u32_e64 s[42:43], 1, v28
	s_andn2_b64 vcc, exec, s[22:23]
	s_waitcnt vmcnt(7)
	v_lshlrev_b32_e32 v114, 16, v20
	v_and_b32_e32 v115, 0xffff0000, v20
	v_lshlrev_b32_e32 v116, 16, v21
	v_and_b32_e32 v117, 0xffff0000, v21
	v_lshlrev_b32_e32 v110, 16, v22
	v_and_b32_e32 v111, 0xffff0000, v22
	v_lshlrev_b32_e32 v112, 16, v23
	v_and_b32_e32 v113, 0xffff0000, v23
	s_waitcnt vmcnt(6)
	v_lshlrev_b32_e32 v106, 16, v24
	v_and_b32_e32 v107, 0xffff0000, v24
	v_lshlrev_b32_e32 v108, 16, v25
	v_and_b32_e32 v109, 0xffff0000, v25
	v_lshlrev_b32_e32 v102, 16, v26
	v_and_b32_e32 v103, 0xffff0000, v26
	v_lshlrev_b32_e32 v104, 16, v27
	v_and_b32_e32 v105, 0xffff0000, v27
	s_cbranch_vccnz .LBB0_361
	v_lshl_add_u64 v[24:25], s[48:49], 0, v[94:95]
	ds_read_b128 v[20:23], v246
	s_waitcnt lgkmcnt(0)
	v_lshlrev_b32_e32 v26, 16, v20
	v_and_b32_e32 v27, 0xffff0000, v20
	v_lshlrev_b32_e32 v28, 16, v21
	v_and_b32_e32 v29, 0xffff0000, v21
	v_mul_f32_e32 v20, 0xbfb8aa3b, v26
	v_mul_f32_e32 v21, 0xbfb8aa3b, v27
	v_exp_f32_e32 v20, v20
	v_exp_f32_e32 v21, v21
	v_lshlrev_b32_e32 v30, 16, v22
	v_and_b32_e32 v22, 0xffff0000, v22
	v_add_f32_e32 v20, 1.0, v20
	v_add_f32_e32 v21, 1.0, v21
	v_rcp_f32_e32 v20, v20
	v_rcp_f32_e32 v21, v21
	v_lshlrev_b32_e32 v31, 16, v23
	v_and_b32_e32 v23, 0xffff0000, v23
	v_pk_mul_f32 v[114:115], v[20:21], v[114:115]
	v_mul_f32_e32 v20, 0xbfb8aa3b, v28
	v_mul_f32_e32 v21, 0xbfb8aa3b, v29
	v_exp_f32_e32 v20, v20
	v_exp_f32_e32 v21, v21
	v_add_f32_e32 v20, 1.0, v20
	v_add_f32_e32 v21, 1.0, v21
	v_rcp_f32_e32 v20, v20
	v_rcp_f32_e32 v21, v21
	s_nop 0
	v_pk_mul_f32 v[116:117], v[20:21], v[116:117]
	v_mul_f32_e32 v20, 0xbfb8aa3b, v30
	v_mul_f32_e32 v21, 0xbfb8aa3b, v22
	v_exp_f32_e32 v20, v20
	v_exp_f32_e32 v21, v21
	v_add_f32_e32 v20, 1.0, v20
	v_add_f32_e32 v21, 1.0, v21
	v_rcp_f32_e32 v20, v20
	v_rcp_f32_e32 v21, v21
	s_nop 0
	v_pk_mul_f32 v[110:111], v[20:21], v[110:111]
	v_mul_f32_e32 v20, 0xbfb8aa3b, v31
	v_mul_f32_e32 v21, 0xbfb8aa3b, v23
	v_exp_f32_e32 v20, v20
	v_exp_f32_e32 v21, v21
	v_add_f32_e32 v20, 1.0, v20
	v_add_f32_e32 v21, 1.0, v21
	v_rcp_f32_e32 v20, v20
	v_rcp_f32_e32 v21, v21
	s_nop 0
	v_pk_mul_f32 v[112:113], v[20:21], v[112:113]
	ds_read_b128 v[20:23], v246 offset:1024
	s_waitcnt lgkmcnt(0)
	v_lshlrev_b32_e32 v24, 16, v20
	v_and_b32_e32 v25, 0xffff0000, v20
	v_lshlrev_b32_e32 v26, 16, v21
	v_and_b32_e32 v27, 0xffff0000, v21
	v_mul_f32_e32 v20, 0xbfb8aa3b, v24
	v_mul_f32_e32 v21, 0xbfb8aa3b, v25
	v_exp_f32_e32 v20, v20
	v_exp_f32_e32 v21, v21
	v_lshlrev_b32_e32 v28, 16, v22
	v_and_b32_e32 v22, 0xffff0000, v22
	v_add_f32_e32 v20, 1.0, v20
	v_add_f32_e32 v21, 1.0, v21
	v_rcp_f32_e32 v20, v20
	v_rcp_f32_e32 v21, v21
	v_lshlrev_b32_e32 v29, 16, v23
	v_and_b32_e32 v23, 0xffff0000, v23
	v_pk_mul_f32 v[106:107], v[20:21], v[106:107]
	v_mul_f32_e32 v20, 0xbfb8aa3b, v26
	v_mul_f32_e32 v21, 0xbfb8aa3b, v27
	v_exp_f32_e32 v20, v20
	v_exp_f32_e32 v21, v21
	v_add_f32_e32 v20, 1.0, v20
	v_add_f32_e32 v21, 1.0, v21
	v_rcp_f32_e32 v20, v20
	v_rcp_f32_e32 v21, v21
	s_nop 0
	v_pk_mul_f32 v[108:109], v[20:21], v[108:109]
	v_mul_f32_e32 v20, 0xbfb8aa3b, v28
	v_mul_f32_e32 v21, 0xbfb8aa3b, v22
	v_exp_f32_e32 v20, v20
	v_exp_f32_e32 v21, v21
	v_add_f32_e32 v20, 1.0, v20
	v_add_f32_e32 v21, 1.0, v21
	v_rcp_f32_e32 v20, v20
	v_rcp_f32_e32 v21, v21
	s_nop 0
	v_pk_mul_f32 v[102:103], v[20:21], v[102:103]
	v_mul_f32_e32 v20, 0xbfb8aa3b, v29
	v_mul_f32_e32 v21, 0xbfb8aa3b, v23
	v_exp_f32_e32 v20, v20
	v_exp_f32_e32 v21, v21
	v_add_f32_e32 v20, 1.0, v20
	v_add_f32_e32 v21, 1.0, v21
	v_rcp_f32_e32 v20, v20
	v_rcp_f32_e32 v21, v21
	s_nop 0
	v_pk_mul_f32 v[104:105], v[20:21], v[104:105]
